# static s_setprio 1 for waves 4-7 (the lagging half) across the sample attention loop, per-iteration priority flips removed
# baseline (speedup 1.0000x reference)
.LBB0_374:
	s_andn2_saveexec_b64 s[0:1], s[0:1]
	v_lshlrev_b64 v[0:1], 10, v[2:3]
	v_lshl_add_u64 v[0:1], s[2:3], 0, v[0:1]
	v_mov_b32_e32 v13, v137
	v_lshl_add_u64 v[0:1], v[0:1], 0, v[12:13]
	s_or_b64 exec, exec, s[0:1]
	s_ashr_i32 s71, s70, 31
	s_lshl_b64 s[0:1], s[70:71], 1
	v_readlane_b32 s4, v252, 63
	v_readlane_b32 s5, v253, 0
	s_add_u32 s0, s4, s0
	s_addc_u32 s1, s5, s1
	v_mov_b32_e32 v15, v137
	global_load_dwordx4 v[104:107], v[0:1], off
	v_lshl_add_u64 v[0:1], s[0:1], 0, v[14:15]
	v_lshl_add_u64 v[2:3], v[0:1], 0, v[136:137]
	v_mov_b32_e32 v121, v137
	v_lshl_add_u64 v[0:1], v[0:1], 0, v[120:121]
	global_load_dwordx4 v[108:111], v[2:3], off
	global_load_dwordx4 v[112:115], v[0:1], off
	v_lshl_add_u64 v[122:123], s[4:5], 0, v[14:15]
	v_readlane_b32 s4, v253, 3
	s_add_i32 s0, s22, 0x2080
	v_mov_b32_e32 v9, v137
	v_readlane_b32 s5, v253, 4
	v_mov_b32_e32 v11, v137
	v_mov_b32_e32 v13, v137
	v_mov_b32_e32 v14, v137
	v_lshlrev_b32_e32 v118, 3, v19
	v_mul_u32_u24_e32 v152, 0x90, v16
	v_mul_u32_u24_e32 v153, 0x90, v17
	v_lshl_add_u32 v154, v19, 4, s24
	v_lshl_add_u64 v[124:125], s[4:5], 0, v[8:9]
	v_lshl_add_u64 v[126:127], s[2:3], 0, v[8:9]
	v_lshl_add_u64 v[128:129], s[4:5], 0, v[10:11]
	v_lshl_add_u64 v[130:131], s[2:3], 0, v[10:11]
	v_lshl_add_u64 v[132:133], s[4:5], 0, v[12:13]
	v_lshl_add_u64 v[134:135], s[2:3], 0, v[12:13]
	v_mul_u32_u24_e32 v155, 0xd0, v18
	v_mul_u32_u24_e32 v142, 0x90, v18
	v_add_u32_sdwa v156, s0, v22 dst_sel:DWORD dst_unused:UNUSED_PAD src0_sel:DWORD src1_sel:WORD_1
	v_add_u32_sdwa v157, s0, v21 dst_sel:DWORD dst_unused:UNUSED_PAD src0_sel:DWORD src1_sel:WORD_1
	v_add_u32_e32 v158, s0, v20
	v_mov_b32_e32 v0, v137
	v_mov_b32_e32 v1, v137
	v_mov_b32_e32 v2, v137
	v_mov_b32_e32 v3, v137
	v_mov_b32_e32 v4, v137
	v_mov_b32_e32 v5, v137
	v_mov_b32_e32 v6, v137
	v_mov_b32_e32 v7, v137
	v_mov_b32_e32 v8, v137
	v_mov_b32_e32 v10, v137
	v_mov_b32_e32 v12, v137
	v_mov_b64_e32 v[30:31], v[14:15]
	v_add_u32_e32 v143, s24, v118
	s_mov_b32 s1, 0
	v_mov_b32_e32 v151, 0xf149f2ca
	v_mov_b32_e32 v119, 0
	v_mov_b64_e32 v[28:29], v[12:13]
	v_mov_b64_e32 v[26:27], v[10:11]
	v_mov_b64_e32 v[24:25], v[8:9]
	v_mov_b64_e32 v[22:23], v[6:7]
	v_mov_b64_e32 v[20:21], v[4:5]
	v_mov_b64_e32 v[18:19], v[2:3]
	v_mov_b64_e32 v[16:17], v[0:1]
	s_mov_b32 s3, 0
	s_movk_i32 s4, 0xff80
	s_mov_b32 s5, -1
	v_mov_b32_e32 v238, 0x1000
	v_mov_b32_e32 v239, 0x10000
	v_add_u32_e32 v32, s1, v158
	v_ashrrev_i32_e32 v33, 31, v32
	v_lshlrev_b64 v[34:35], 10, v[32:33]
	v_lshlrev_b64 v[32:33], 6, v[32:33]
	v_lshl_add_u64 v[32:33], v[124:125], 0, v[32:33]
	v_lshl_add_u64 v[34:35], v[126:127], 0, v[34:35]
	v_lshl_add_u64 v[32:33], v[32:33], 0, s[4:5]
	v_cndmask_b32_e64 v241, v33, v35, s[40:41]
	v_cndmask_b32_e64 v240, v32, v34, s[40:41]
	v_add_u32_e32 v32, s1, v157
	v_ashrrev_i32_e32 v33, 31, v32
	v_lshlrev_b64 v[34:35], 10, v[32:33]
	v_lshlrev_b64 v[32:33], 6, v[32:33]
	v_lshl_add_u64 v[32:33], v[128:129], 0, v[32:33]
	v_lshl_add_u64 v[34:35], v[130:131], 0, v[34:35]
	v_lshl_add_u64 v[32:33], v[32:33], 0, s[4:5]
	v_cndmask_b32_e64 v243, v33, v35, s[42:43]
	v_cndmask_b32_e64 v242, v32, v34, s[42:43]
	v_add_u32_e32 v32, s1, v156
	v_ashrrev_i32_e32 v33, 31, v32
	v_lshlrev_b64 v[34:35], 10, v[32:33]
	v_lshlrev_b64 v[32:33], 6, v[32:33]
	v_lshl_add_u64 v[32:33], v[132:133], 0, v[32:33]
	v_lshl_add_u64 v[34:35], v[134:135], 0, v[34:35]
	v_lshl_add_u64 v[32:33], v[32:33], 0, s[4:5]
	v_cndmask_b32_e64 v245, v33, v35, s[44:45]
	v_cndmask_b32_e64 v244, v32, v34, s[44:45]
	s_add_i32 s22, s0, s1
	s_ashr_i32 s23, s22, 31
	v_lshl_add_u64 v[32:33], s[22:23], 1, v[122:123]
	v_lshl_add_u64 v[246:247], v[32:33], 0, v[136:137]
	v_mov_b32_e32 v121, v137
	v_lshl_add_u64 v[248:249], v[32:33], 0, v[120:121]
	v_mov_b32_e32 v120, 0
	v_mov_b32_e32 v121, 0
	v_mov_b32_e32 v122, 0
	v_mov_b32_e32 v123, 0
	v_mov_b32_e32 v124, 0
	v_mov_b32_e32 v125, 0
	v_mov_b32_e32 v126, 0
	v_mov_b32_e32 v127, 0
	v_mov_b32_e32 v128, 0
	v_mov_b32_e32 v129, 0
	v_mov_b32_e32 v130, 0
	v_mov_b32_e32 v131, 0
	v_mov_b32_e32 v132, 0
	v_mov_b32_e32 v133, 0
	v_mov_b32_e32 v134, 0
	v_mov_b32_e32 v135, 0
	s_waitcnt lgkmcnt(0)
	s_barrier
	v_readfirstlane_b32 s22, v139
	s_bitcmp1_b32 s22, 8
	s_cbranch_scc0 .Lsa_no_e1
	s_barrier
	s_setprio 1

.LBB0_383:
	s_setprio 0
	v_readfirstlane_b32 s22, v139
	s_bitcmp1_b32 s22, 8
	s_cbranch_scc1 .Lsa_no_e0
	s_barrier
